# scan helper: nt (streaming) hint on the 28 per-step chunk staging loads, each cache line is touched by exactly one load instruction; on top of helper priority raise and attention permlane max
# baseline (speedup 1.0000x reference)
; DI void sh_load(const ScanH& k, int nc, u32x4 (&st)[14]) {
;     const size_t o8 = (size_t)nc * 8192; const int ht = k.ht;
; #pragma unroll
;     for (int i = 0; i < 4; ++i) { const int id = ht + 256 * i, r = id >> 4, cc = id & 15; st[i] = *(const u32x4*)(k.WC + o8 + r * 128 + cc * 8); st[4 + i] = *(const u32x4*)(k.QD + o8 + r * 128 + cc * 8); }
; #pragma unroll
;     for (int i = 0; i < 4; ++i) { const int id = ht + 256 * i, r = id >> 3, cc = id & 7; st[8 + i] = *(const u32x4*)(k.KD + o8 + r * 64 + cc * 8); }
; #pragma unroll
;     for (int i = 0; i < 2; ++i) { const int id = ht + 256 * i, r = id >> 3, cc = id & 7; st[12 + i] = *(const u32x4*)(k.AT + (size_t)nc * 4096 + r * 64 + cc * 8); }
; }
; DI void sh_store(const ScanH& k, int bf, const u32x4 (&st)[14]) {
;     LAS unsigned char* B_ = k.lds + bf * SC_BUF; const int ht = k.ht;
; #pragma unroll
;     for (int i = 0; i < 4; ++i) { const int id = ht + 256 * i, r = id >> 4, cc = id & 15;
;         *(LAS u32x2*)(B_ + SC_W + r * 264 + cc * 16) = (u32x2){st[i].x, st[i].y}; *(LAS u32x2*)(B_ + SC_W + r * 264 + cc * 16 + 8) = (u32x2){st[i].z, st[i].w};
;         *(LAS u32x2*)(B_ + SC_Q + r * 264 + cc * 16) = (u32x2){st[4 + i].x, st[4 + i].y}; *(LAS u32x2*)(B_ + SC_Q + r * 264 + cc * 16 + 8) = (u32x2){st[4 + i].z, st[4 + i].w}; }
; #pragma unroll
;     for (int i = 0; i < 4; ++i) { const int id = ht + 256 * i, r = id >> 3, cc = id & 7;
;         *(LAS u32x2*)(B_ + SC_K + r * 136 + cc * 16) = (u32x2){st[8 + i].x, st[8 + i].y}; *(LAS u32x2*)(B_ + SC_K + r * 136 + cc * 16 + 8) = (u32x2){st[8 + i].z, st[8 + i].w}; }
; #pragma unroll
;     for (int i = 0; i < 2; ++i) { const int id = ht + 256 * i, r = id >> 3, cc = id & 7;
;         *(LAS u32x2*)(B_ + SC_A + r * 136 + cc * 16) = (u32x2){st[12 + i].x, st[12 + i].y}; *(LAS u32x2*)(B_ + SC_A + r * 136 + cc * 16 + 8) = (u32x2){st[12 + i].z, st[12 + i].w}; }
; }
; DI void scan_helper_step(const ScanH& k, int n, u32x4 (&stL)[14], const u32x4 (&stS)[14]) {
;     LAS unsigned char* lds = k.lds; const int bf = n & 1, tokb = k.b * SEQ + n * 64;
;     u32x4 zz[4];
;     { const bf16_t* zp = k.Zg + (size_t)(tokb + k.pt) * 512 + k.h * 128 + 32 * k.pseg;
; #pragma unroll
;       for (int i = 0; i < 4; ++i) zz[i] = *(const u32x4*)(zp + 8 * i); }
;     sh_load(k, n + 2 < 128 ? n + 2 : 127, stL);
;     sh_store(k, bf ^ 1, stS);
;     SC_RAW_BARRIER();
.LBB0_198:
	v_ashrrev_i32_e32 v151, 31, v150
	v_add_u32_e32 v58, 64, v150
	v_ashrrev_i32_e32 v59, 31, v58
	v_lshlrev_b64 v[58:59], 10, v[58:59]
	v_lshl_add_u64 v[58:59], v[152:153], 0, v[58:59]
	global_load_dwordx4 v[236:239], v[58:59], off offset:48
	global_load_dwordx4 v[240:243], v[58:59], off offset:32
	global_load_dwordx4 v[244:247], v[58:59], off offset:16
	global_load_dwordx4 v[248:251], v[58:59], off
	s_add_i32 s24, s40, 2
	v_add_u32_e32 v186, 0xea00, v159
	s_min_u32 s14, s24, 0x7d
	s_waitcnt vmcnt(17)
	ds_write2_b64 v186, v[2:3], v[4:5] offset1:1
	v_add_u32_e32 v2, v180, v158
	s_lshl_b32 s41, s14, 13
	s_waitcnt vmcnt(16)
	ds_write2_b64 v2, v[10:11], v[12:13] offset1:1
	v_add_u32_e32 v2, 0xea00, v162
	s_addk_i32 s41, 0x4000
	s_waitcnt vmcnt(15)
	ds_write2_b64 v2, v[6:7], v[8:9] offset1:1
	v_add_u32_e32 v2, v180, v161
	s_lshl_b32 s44, s41, 1
	s_waitcnt vmcnt(14)
	ds_write2_b64 v2, v[18:19], v[20:21] offset1:1
	v_add_u32_e32 v2, 0xea00, v165
	s_add_u32 s14, s4, s44
	s_waitcnt vmcnt(13)
	ds_write2_b64 v2, v[14:15], v[16:17] offset1:1
	v_add_u32_e32 v2, v180, v164
	s_addc_u32 s15, s5, 0
	s_waitcnt vmcnt(12)
	ds_write2_b64 v2, v[26:27], v[28:29] offset1:1
	v_add_u32_e32 v2, 0xea00, v168
	s_add_u32 s42, s6, s44
	s_waitcnt vmcnt(11)
	ds_write2_b64 v2, v[22:23], v[24:25] offset1:1
	v_add_u32_e32 v2, v180, v167
	s_addc_u32 s43, s7, 0
	s_waitcnt vmcnt(10)
	ds_write2_b64 v2, v[30:31], v[32:33] offset1:1
	v_add_u32_e32 v2, v181, v170
	v_lshl_add_u64 v[58:59], s[14:15], 0, v[134:135]
	v_lshl_add_u64 v[66:67], s[14:15], 0, v[136:137]
	v_lshl_add_u64 v[74:75], s[14:15], 0, v[138:139]
	v_lshl_add_u64 v[82:83], s[14:15], 0, v[140:141]
	s_add_u32 s14, s8, s44
	s_waitcnt vmcnt(9)
	ds_write2_b64 v2, v[34:35], v[36:37] offset1:1
	v_add_u32_e32 v2, v181, v172
	s_addc_u32 s15, s9, 0
	s_waitcnt vmcnt(8)
	ds_write2_b64 v2, v[38:39], v[40:41] offset1:1
	v_add_u32_e32 v2, v181, v174
	v_lshl_add_u64 v[90:91], s[14:15], 0, v[142:143]
	v_lshl_add_u64 v[94:95], s[14:15], 0, v[144:145]
	v_lshl_add_u64 v[98:99], s[14:15], 0, v[146:147]
	v_lshl_add_u64 v[102:103], s[14:15], 0, v[148:149]
	s_add_u32 s14, s10, s41
	s_waitcnt vmcnt(7)
	ds_write2_b64 v2, v[42:43], v[44:45] offset1:1
	v_add_u32_e32 v2, v181, v176
	s_addc_u32 s15, s11, 0
	s_waitcnt vmcnt(6)
	ds_write2_b64 v2, v[46:47], v[48:49] offset1:1
	v_add_u32_e32 v2, v182, v170
	v_lshl_add_u64 v[62:63], s[42:43], 0, v[134:135]
	v_lshl_add_u64 v[70:71], s[42:43], 0, v[136:137]
	v_lshl_add_u64 v[78:79], s[42:43], 0, v[138:139]
	v_lshl_add_u64 v[86:87], s[42:43], 0, v[140:141]
	v_mov_b32_e32 v157, v1
	v_lshl_add_u64 v[106:107], s[14:15], 0, v[142:143]
	v_lshl_add_u64 v[110:111], s[14:15], 0, v[144:145]
	s_waitcnt vmcnt(5)
	ds_write2_b64 v2, v[50:51], v[52:53] offset1:1
	v_add_u32_e32 v2, v182, v172
	v_lshl_add_u64 v[58:59], v[58:59], 0, v[0:1]
	v_lshl_add_u64 v[62:63], v[62:63], 0, v[0:1]
	v_lshl_add_u64 v[66:67], v[66:67], 0, v[0:1]
	v_lshl_add_u64 v[70:71], v[70:71], 0, v[0:1]
	v_lshl_add_u64 v[74:75], v[74:75], 0, v[0:1]
	v_lshl_add_u64 v[78:79], v[78:79], 0, v[0:1]
	v_lshl_add_u64 v[82:83], v[82:83], 0, v[0:1]
	v_lshl_add_u64 v[86:87], v[86:87], 0, v[0:1]
	v_lshl_add_u64 v[90:91], v[90:91], 0, v[156:157]
	v_lshl_add_u64 v[94:95], v[94:95], 0, v[156:157]
	v_lshl_add_u64 v[98:99], v[98:99], 0, v[156:157]
	v_lshl_add_u64 v[102:103], v[102:103], 0, v[156:157]
	v_lshl_add_u64 v[106:107], v[106:107], 0, v[156:157]
	v_lshl_add_u64 v[110:111], v[110:111], 0, v[156:157]
	s_waitcnt vmcnt(4)
	ds_write2_b64 v2, v[54:55], v[56:57] offset1:1
	global_load_dwordx4 v[58:61], v[58:59], off nt
	s_add_i32 s14, s40, 3
	global_load_dwordx4 v[62:65], v[62:63], off nt
	s_min_u32 s14, s14, 0x7d
	global_load_dwordx4 v[66:69], v[66:67], off nt
	s_lshl_b32 s14, s14, 13
	global_load_dwordx4 v[70:73], v[70:71], off nt
	v_lshlrev_b32_e32 v228, 16, v118
	global_load_dwordx4 v[74:77], v[74:75], off nt
	v_and_b32_e32 v229, 0xffff0000, v118
	global_load_dwordx4 v[78:81], v[78:79], off nt
	v_lshlrev_b32_e32 v56, 16, v128
	global_load_dwordx4 v[82:85], v[82:83], off nt
	v_and_b32_e32 v57, 0xffff0000, v128
	global_load_dwordx4 v[86:89], v[86:87], off nt
	v_lshlrev_b32_e32 v192, 16, v127
	global_load_dwordx4 v[90:93], v[90:91], off nt
	v_and_b32_e32 v193, 0xffff0000, v127
	global_load_dwordx4 v[94:97], v[94:95], off nt
	v_lshlrev_b32_e32 v202, 16, v126
	global_load_dwordx4 v[98:101], v[98:99], off nt
	v_and_b32_e32 v203, 0xffff0000, v126
	global_load_dwordx4 v[102:105], v[102:103], off nt
	v_lshlrev_b32_e32 v126, 16, v129
	global_load_dwordx4 v[106:109], v[106:107], off nt
	v_and_b32_e32 v127, 0xffff0000, v129
	global_load_dwordx4 v[110:113], v[110:111], off nt
	s_waitcnt lgkmcnt(0)
	s_barrier
; #define LAS __attribute__((address_space(3)))
; DI unsigned pk2(float lo, float hi) { f32x2 v = {lo, hi}; bf16x2_t b = __builtin_convertvector(v, bf16x2_t); return __builtin_bit_cast(unsigned, b); }
; DI float lo_bf(unsigned u) { return __uint_as_float(u << 16); }
; DI float hi_bf(unsigned u) { return __uint_as_float(u & 0xffff0000u); }
; DI void scan_helper_step(const ScanH& k, int n, u32x4 (&stL)[14], const u32x4 (&stS)[14]) {
;     ...
;     const LAS unsigned char* ob = lds + SC_O + bf * SC_OSZ + k.pt * 272 + k.pseg * 64;
;     const LAS float* gmL = (const LAS float*)(lds + SC_O + 2 * SC_OSZ + 512) + 32 * k.pseg;
;     u32x4 ov4[4];
; #pragma unroll
;     for (int i = 0; i < 4; ++i) ov4[i] = *(const LAS u32x4*)(ob + 16 * i);
;     float ss = 0.f;
; #pragma unroll
;     for (int i = 0; i < 4; ++i)
; #pragma unroll
;         for (int j = 0; j < 4; ++j) { const float a = lo_bf(ov4[i][j]), b2 = hi_bf(ov4[i][j]); ss += a * a + b2 * b2; }
;     ss += __shfl_xor(ss, 1); ss += __shfl_xor(ss, 2);
;     const float rs = __builtin_amdgcn_rsqf(ss * (1.f / 128.f) + RMS_EPS);
;     bf16_t* mp = k.MIX + (size_t)(tokb + k.pt) * DM + k.h * 128 + 32 * k.pseg;
; #pragma unroll
;     for (int i = 0; i < 4; ++i) { u32x4 res;
; #pragma unroll
;         for (int j = 0; j < 4; ++j) { const int e = 8 * i + 2 * j;
;             const float a0 = lo_bf(ov4[i][j]) * rs * gmL[e] * lo_bf(zz[i][j]), a1 = hi_bf(ov4[i][j]) * rs * gmL[e + 1] * hi_bf(zz[i][j]); res[j] = pk2(a0, a1); }
;         *(u32x4*)(mp + 8 * i) = res; }
	ds_read_b128 v[14:17], v183
	ds_read_b128 v[18:21], v183 offset:16
	ds_read_b128 v[22:25], v183 offset:32
	ds_read_b128 v[2:5], v183 offset:48
	v_lshlrev_b32_e32 v210, 16, v124
	s_waitcnt lgkmcnt(3)
	v_lshlrev_b32_e32 v188, 16, v15
	v_and_b32_e32 v189, 0xffff0000, v15
	s_waitcnt lgkmcnt(1)
	v_and_b32_e32 v13, 0xffff0000, v25
	v_and_b32_e32 v12, 0xffff0000, v24
	v_lshlrev_b32_e32 v11, 16, v25
	v_lshlrev_b32_e32 v10, 16, v24
	v_pk_mul_f32 v[6:7], v[12:13], v[12:13]
	s_waitcnt lgkmcnt(0)
	v_and_b32_e32 v9, 0xffff0000, v3
	v_and_b32_e32 v8, 0xffff0000, v2
	v_pk_fma_f32 v[40:41], v[10:11], v[10:11], v[6:7]
	v_lshlrev_b32_e32 v7, 16, v3
	v_lshlrev_b32_e32 v6, 16, v2
	v_pk_mul_f32 v[2:3], v[8:9], v[8:9]
	v_lshlrev_b32_e32 v198, 16, v14
	v_pk_fma_f32 v[42:43], v[6:7], v[6:7], v[2:3]
	v_lshlrev_b32_e32 v3, 16, v5
	v_lshlrev_b32_e32 v2, 16, v4
	v_and_b32_e32 v5, 0xffff0000, v5
	v_and_b32_e32 v4, 0xffff0000, v4
	v_pk_mul_f32 v[24:25], v[4:5], v[4:5]
	v_and_b32_e32 v199, 0xffff0000, v14
	v_pk_fma_f32 v[44:45], v[2:3], v[2:3], v[24:25]
	v_and_b32_e32 v25, 64, v230
	v_xor_b32_e32 v24, 1, v230
	v_add_u32_e32 v25, 64, v25
	v_cmp_lt_i32_e32 vcc, v24, v25
	v_lshlrev_b32_e32 v52, 16, v16
	v_and_b32_e32 v53, 0xffff0000, v16
	v_cndmask_b32_e32 v24, v230, v24, vcc
	v_lshlrev_b32_e32 v186, 2, v24
	v_xor_b32_e32 v24, 2, v230
	v_cmp_lt_i32_e32 vcc, v24, v25
	v_pk_mul_f32 v[190:191], v[188:189], v[188:189]
	v_pk_mul_f32 v[200:201], v[198:199], v[198:199]
	v_cndmask_b32_e32 v24, v230, v24, vcc
	v_lshlrev_b32_e32 v187, 2, v24
	v_lshlrev_b64 v[24:25], 11, v[150:151]
	v_lshlrev_b32_e32 v48, 16, v17
	v_and_b32_e32 v49, 0xffff0000, v17
	v_pk_mul_f32 v[54:55], v[52:53], v[52:53]
	v_add_f32_e32 v118, v190, v191
	v_add_f32_e32 v151, v200, v201
	v_pk_mul_f32 v[50:51], v[48:49], v[48:49]
	v_lshlrev_b32_e32 v218, 16, v18
	v_and_b32_e32 v219, 0xffff0000, v18
	v_add_f32_e32 v118, v151, v118
	v_add_f32_e32 v54, v54, v55
	v_lshlrev_b32_e32 v212, 16, v19
	v_and_b32_e32 v213, 0xffff0000, v19
	v_pk_mul_f32 v[18:19], v[218:219], v[218:219]
	v_add_f32_e32 v54, v54, v118
	v_add_f32_e32 v50, v50, v51
	v_lshlrev_b32_e32 v208, 16, v20
	v_and_b32_e32 v209, 0xffff0000, v20
	v_pk_mul_f32 v[214:215], v[212:213], v[212:213]
	v_add_f32_e32 v50, v50, v54
	v_add_f32_e32 v18, v18, v19
	v_lshlrev_b32_e32 v128, 16, v21
	v_and_b32_e32 v129, 0xffff0000, v21
	v_pk_mul_f32 v[20:21], v[208:209], v[208:209]
	v_add_f32_e32 v18, v18, v50
	v_add_f32_e32 v19, v214, v215
	v_pk_mul_f32 v[204:205], v[128:129], v[128:129]
	v_lshlrev_b32_e32 v224, 16, v22
	v_and_b32_e32 v225, 0xffff0000, v22
	v_add_f32_e32 v18, v19, v18
	v_add_f32_e32 v19, v20, v21
	v_and_b32_e32 v211, 0xffff0000, v124
	v_lshlrev_b32_e32 v216, 16, v123
	v_and_b32_e32 v217, 0xffff0000, v123
	v_lshlrev_b32_e32 v220, 16, v122
	v_and_b32_e32 v221, 0xffff0000, v122
	v_lshlrev_b32_e32 v122, 16, v125
	v_and_b32_e32 v123, 0xffff0000, v125
	v_lshlrev_b32_e32 v124, 16, v23
	v_and_b32_e32 v125, 0xffff0000, v23
	v_pk_mul_f32 v[22:23], v[224:225], v[224:225]
	v_add_f32_e32 v18, v19, v18
	v_add_f32_e32 v19, v204, v205
	v_pk_mul_f32 v[222:223], v[124:125], v[124:125]
	v_add_f32_e32 v18, v19, v18
	v_add_f32_e32 v19, v22, v23
	v_add_f32_e32 v18, v19, v18
	v_add_f32_e32 v19, v222, v223
	v_add_f32_e32 v18, v19, v18
	v_add_f32_e32 v18, v40, v18
	v_add_f32_e32 v18, v41, v18
	v_add_f32_e32 v18, v42, v18
	v_add_f32_e32 v18, v43, v18
	v_add_f32_e32 v18, v44, v18
	v_add_f32_e32 v18, v45, v18
	s_nop 1
	v_mov_b32_dpp v19, v18 quad_perm:[1,0,3,2] row_mask:0xf bank_mask:0xf
	v_lshl_add_u64 v[46:47], v[154:155], 0, v[24:25]
	ds_read_b128 v[24:27], v184
	ds_read_b128 v[28:31], v184 offset:16
	ds_read_b128 v[32:35], v184 offset:32
	ds_read_b128 v[36:39], v184 offset:48
	ds_read_b128 v[14:17], v184 offset:64
	ds_read_b128 v[130:133], v184 offset:80
	ds_read_b128 v[194:197], v184 offset:96
	ds_read_b128 v[232:235], v184 offset:112
	s_add_i32 s42, s14, 0x4000
	s_waitcnt lgkmcnt(5)
	v_add_f32_e32 v18, v18, v19
	s_nop 1
	v_mov_b32_dpp v19, v18 quad_perm:[2,3,0,1] row_mask:0xf bank_mask:0xf
	s_lshl_b32 s43, s42, 1
	s_add_u32 s14, s4, s43
	s_addc_u32 s15, s5, 0
	s_add_u32 s40, s6, s43
	s_waitcnt lgkmcnt(0)
	v_add_f32_e32 v18, v18, v19
	v_fmamk_f32 v18, v18, 0x3c000000, v231
	v_rsq_f32_e32 v22, v18
	s_addc_u32 s41, s7, 0
	v_pk_mul_f32 v[18:19], v[22:23], v[198:199] op_sel_hi:[0,1]
	v_pk_mul_f32 v[20:21], v[22:23], v[188:189] op_sel_hi:[0,1]
	v_pk_mul_f32 v[18:19], v[24:25], v[18:19]
	v_pk_mul_f32 v[20:21], v[26:27], v[20:21]
	v_pk_mul_f32 v[18:19], v[18:19], v[202:203]
	v_pk_mul_f32 v[20:21], v[20:21], v[192:193]
	v_cvt_pk_bf16_f32 v18, v18, v19
	v_cvt_pk_bf16_f32 v19, v20, v21
	v_pk_mul_f32 v[20:21], v[22:23], v[52:53] op_sel_hi:[0,1]
	v_pk_mul_f32 v[24:25], v[22:23], v[48:49] op_sel_hi:[0,1]
	v_pk_mul_f32 v[20:21], v[28:29], v[20:21]
	v_pk_mul_f32 v[24:25], v[30:31], v[24:25]
	v_pk_mul_f32 v[20:21], v[20:21], v[56:57]
	v_pk_mul_f32 v[24:25], v[24:25], v[126:127]
	v_cvt_pk_bf16_f32 v20, v20, v21
	v_cvt_pk_bf16_f32 v21, v24, v25
	global_store_dwordx4 v[46:47], v[18:21], off
	v_pk_mul_f32 v[24:25], v[22:23], v[128:129] op_sel_hi:[0,1]
	v_pk_mul_f32 v[24:25], v[38:39], v[24:25]
	v_pk_mul_f32 v[18:19], v[22:23], v[218:219] op_sel_hi:[0,1]
	v_pk_mul_f32 v[20:21], v[22:23], v[212:213] op_sel_hi:[0,1]
	v_pk_mul_f32 v[18:19], v[32:33], v[18:19]
	v_pk_mul_f32 v[20:21], v[34:35], v[20:21]
	v_pk_mul_f32 v[18:19], v[18:19], v[220:221]
	v_pk_mul_f32 v[20:21], v[20:21], v[216:217]
	v_cvt_pk_bf16_f32 v18, v18, v19
	v_cvt_pk_bf16_f32 v19, v20, v21
	v_pk_mul_f32 v[20:21], v[22:23], v[208:209] op_sel_hi:[0,1]
	v_pk_mul_f32 v[20:21], v[36:37], v[20:21]
	v_pk_mul_f32 v[24:25], v[24:25], v[122:123]
	v_pk_mul_f32 v[20:21], v[20:21], v[210:211]
	v_add_u32_e32 v188, 64, v150
	v_cvt_pk_bf16_f32 v20, v20, v21
	v_cvt_pk_bf16_f32 v21, v24, v25
	global_store_dwordx4 v[46:47], v[18:21], off offset:16
	v_ashrrev_i32_e32 v189, 31, v188
	v_lshl_add_u64 v[30:31], s[40:41], 0, v[140:141]
	v_pk_mul_f32 v[18:19], v[22:23], v[224:225] op_sel_hi:[0,1]
	v_pk_mul_f32 v[14:15], v[18:19], v[14:15]
	v_pk_mul_f32 v[18:19], v[22:23], v[124:125] op_sel_hi:[0,1]
	v_pk_mul_f32 v[16:17], v[18:19], v[16:17]
	v_lshlrev_b32_e32 v18, 16, v119
	v_and_b32_e32 v19, 0xffff0000, v119
	v_pk_mul_f32 v[14:15], v[14:15], v[228:229]
	v_pk_mul_f32 v[16:17], v[16:17], v[18:19]
	v_cvt_pk_bf16_f32 v14, v14, v15
	v_cvt_pk_bf16_f32 v15, v16, v17
	v_mov_b32_e32 v16, v10
	v_mov_b32_e32 v17, v12
	v_pk_mul_f32 v[20:21], v[22:23], v[16:17] op_sel_hi:[0,1]
	v_mov_b32_e32 v12, v11
	v_pk_mul_f32 v[10:11], v[22:23], v[12:13] op_sel_hi:[0,1]
	v_lshlrev_b32_e32 v12, 16, v121
	v_and_b32_e32 v13, 0xffff0000, v121
	s_waitcnt lgkmcnt(0)
; DI void sh_load(const ScanH& k, int nc, u32x4 (&st)[14]) {
;     const size_t o8 = (size_t)nc * 8192; const int ht = k.ht;
; #pragma unroll
;     for (int i = 0; i < 4; ++i) { const int id = ht + 256 * i, r = id >> 4, cc = id & 15; st[i] = *(const u32x4*)(k.WC + o8 + r * 128 + cc * 8); st[4 + i] = *(const u32x4*)(k.QD + o8 + r * 128 + cc * 8); }
; #pragma unroll
;     for (int i = 0; i < 4; ++i) { const int id = ht + 256 * i, r = id >> 3, cc = id & 7; st[8 + i] = *(const u32x4*)(k.KD + o8 + r * 64 + cc * 8); }
; #pragma unroll
;     for (int i = 0; i < 2; ++i) { const int id = ht + 256 * i, r = id >> 3, cc = id & 7; st[12 + i] = *(const u32x4*)(k.AT + (size_t)nc * 4096 + r * 64 + cc * 8); }
; }
; DI void sh_store(const ScanH& k, int bf, const u32x4 (&st)[14]) {
;     LAS unsigned char* B_ = k.lds + bf * SC_BUF; const int ht = k.ht;
; #pragma unroll
;     for (int i = 0; i < 4; ++i) { const int id = ht + 256 * i, r = id >> 4, cc = id & 15;
;         *(LAS u32x2*)(B_ + SC_W + r * 264 + cc * 16) = (u32x2){st[i].x, st[i].y}; *(LAS u32x2*)(B_ + SC_W + r * 264 + cc * 16 + 8) = (u32x2){st[i].z, st[i].w};
;         *(LAS u32x2*)(B_ + SC_Q + r * 264 + cc * 16) = (u32x2){st[4 + i].x, st[4 + i].y}; *(LAS u32x2*)(B_ + SC_Q + r * 264 + cc * 16 + 8) = (u32x2){st[4 + i].z, st[4 + i].w}; }
; #pragma unroll
;     for (int i = 0; i < 4; ++i) { const int id = ht + 256 * i, r = id >> 3, cc = id & 7;
;         *(LAS u32x2*)(B_ + SC_K + r * 136 + cc * 16) = (u32x2){st[8 + i].x, st[8 + i].y}; *(LAS u32x2*)(B_ + SC_K + r * 136 + cc * 16 + 8) = (u32x2){st[8 + i].z, st[8 + i].w}; }
; #pragma unroll
;     for (int i = 0; i < 2; ++i) { const int id = ht + 256 * i, r = id >> 3, cc = id & 7;
;         *(LAS u32x2*)(B_ + SC_A + r * 136 + cc * 16) = (u32x2){st[12 + i].x, st[12 + i].y}; *(LAS u32x2*)(B_ + SC_A + r * 136 + cc * 16 + 8) = (u32x2){st[12 + i].z, st[12 + i].w}; }
; }
; DI void scan_helper_step(const ScanH& k, int n, u32x4 (&stL)[14], const u32x4 (&stS)[14]) {
;     ...
;     bf16_t* mp = k.MIX + (size_t)(tokb + k.pt) * DM + k.h * 128 + 32 * k.pseg;
; #pragma unroll
;     for (int i = 0; i < 4; ++i) { u32x4 res;
; #pragma unroll
;         for (int j = 0; j < 4; ++j) { const int e = 8 * i + 2 * j;
;             const float a0 = lo_bf(ov4[i][j]) * rs * gmL[e] * lo_bf(zz[i][j]), a1 = hi_bf(ov4[i][j]) * rs * gmL[e + 1] * hi_bf(zz[i][j]); res[j] = pk2(a0, a1); }
	v_pk_mul_f32 v[16:17], v[20:21], v[130:131]
	v_lshlrev_b32_e32 v20, 16, v120
	v_and_b32_e32 v21, 0xffff0000, v120
	v_pk_mul_f32 v[10:11], v[10:11], v[132:133]
	v_pk_mul_f32 v[16:17], v[16:17], v[20:21]
	v_pk_mul_f32 v[10:11], v[10:11], v[12:13]
	v_cvt_pk_bf16_f32 v16, v16, v17
	v_cvt_pk_bf16_f32 v17, v10, v11
	v_mov_b32_e32 v10, v6
	v_mov_b32_e32 v11, v8
	global_store_dwordx4 v[46:47], v[14:17], off offset:32
	v_mov_b32_e32 v8, v7
	v_pk_mul_f32 v[8:9], v[22:23], v[8:9] op_sel_hi:[0,1]
	v_pk_mul_f32 v[14:15], v[22:23], v[10:11] op_sel_hi:[0,1]
	v_lshl_add_u64 v[30:31], v[30:31], 0, v[0:1]
	v_add_u32_e32 v150, 0x80, v150
	s_waitcnt lgkmcnt(0)
	v_pk_mul_f32 v[10:11], v[14:15], v[194:195]
	v_lshlrev_b32_e32 v14, 16, v114
	v_and_b32_e32 v15, 0xffff0000, v114
	v_pk_mul_f32 v[10:11], v[10:11], v[14:15]
	v_pk_mul_f32 v[8:9], v[8:9], v[196:197]
	v_cvt_pk_bf16_f32 v6, v10, v11
	v_lshlrev_b32_e32 v10, 16, v115
	v_and_b32_e32 v11, 0xffff0000, v115
	v_pk_mul_f32 v[8:9], v[8:9], v[10:11]
	v_lshl_add_u64 v[14:15], s[40:41], 0, v[136:137]
	v_cvt_pk_bf16_f32 v7, v8, v9
	v_mov_b32_e32 v8, v2
	v_mov_b32_e32 v9, v4
	v_pk_mul_f32 v[12:13], v[22:23], v[8:9] op_sel_hi:[0,1]
	v_mov_b32_e32 v4, v3
	v_pk_mul_f32 v[2:3], v[22:23], v[4:5] op_sel_hi:[0,1]
	v_lshlrev_b32_e32 v4, 16, v117
	v_and_b32_e32 v5, 0xffff0000, v117
	s_waitcnt lgkmcnt(0)
	v_pk_mul_f32 v[8:9], v[12:13], v[232:233]
	v_lshlrev_b32_e32 v12, 16, v116
	v_and_b32_e32 v13, 0xffff0000, v116
	v_pk_mul_f32 v[2:3], v[2:3], v[234:235]
	v_pk_mul_f32 v[8:9], v[8:9], v[12:13]
	v_pk_mul_f32 v[2:3], v[2:3], v[4:5]
	v_cvt_pk_bf16_f32 v8, v8, v9
	v_cvt_pk_bf16_f32 v9, v2, v3
	v_add_u32_e32 v2, 64, v188
	v_ashrrev_i32_e32 v3, 31, v2
	v_lshlrev_b64 v[2:3], 10, v[2:3]
	global_store_dwordx4 v[46:47], v[6:9], off offset:48
	v_lshl_add_u64 v[2:3], v[152:153], 0, v[2:3]
	global_load_dwordx4 v[114:117], v[2:3], off offset:48
	global_load_dwordx4 v[118:121], v[2:3], off offset:32
	global_load_dwordx4 v[122:125], v[2:3], off offset:16
	global_load_dwordx4 v[126:129], v[2:3], off
	v_lshl_add_u64 v[2:3], s[14:15], 0, v[134:135]
	v_lshl_add_u64 v[6:7], s[40:41], 0, v[134:135]
	v_lshl_add_u64 v[2:3], v[2:3], 0, v[0:1]
	v_lshl_add_u64 v[6:7], v[6:7], 0, v[0:1]
	global_load_dwordx4 v[2:5], v[2:3], off nt
	v_lshl_add_u64 v[14:15], v[14:15], 0, v[0:1]
	global_load_dwordx4 v[10:13], v[6:7], off nt
	v_lshl_add_u64 v[6:7], s[14:15], 0, v[136:137]
	v_lshl_add_u64 v[6:7], v[6:7], 0, v[0:1]
	global_load_dwordx4 v[6:9], v[6:7], off nt
	v_lshl_add_u64 v[22:23], s[40:41], 0, v[138:139]
	global_load_dwordx4 v[18:21], v[14:15], off nt
	v_lshl_add_u64 v[14:15], s[14:15], 0, v[138:139]
	v_lshl_add_u64 v[14:15], v[14:15], 0, v[0:1]
	v_lshl_add_u64 v[22:23], v[22:23], 0, v[0:1]
	global_load_dwordx4 v[14:17], v[14:15], off nt
	s_mov_b32 s40, s24
	global_load_dwordx4 v[26:29], v[22:23], off nt
	v_lshl_add_u64 v[22:23], s[14:15], 0, v[140:141]
	s_add_u32 s14, s8, s43
	s_addc_u32 s15, s9, 0
	v_lshl_add_u64 v[34:35], s[14:15], 0, v[142:143]
	v_lshl_add_u64 v[38:39], s[14:15], 0, v[144:145]
	v_lshl_add_u64 v[42:43], s[14:15], 0, v[146:147]
	v_lshl_add_u64 v[46:47], s[14:15], 0, v[148:149]
	s_add_u32 s14, s10, s42
	s_addc_u32 s15, s11, 0
	v_lshl_add_u64 v[50:51], s[14:15], 0, v[142:143]
	v_lshl_add_u64 v[54:55], s[14:15], 0, v[144:145]
	v_lshl_add_u64 v[22:23], v[22:23], 0, v[0:1]
	v_lshl_add_u64 v[34:35], v[34:35], 0, v[156:157]
	v_lshl_add_u64 v[38:39], v[38:39], 0, v[156:157]
	v_lshl_add_u64 v[42:43], v[42:43], 0, v[156:157]
	v_lshl_add_u64 v[46:47], v[46:47], 0, v[156:157]
	v_lshl_add_u64 v[50:51], v[50:51], 0, v[156:157]
	v_lshl_add_u64 v[54:55], v[54:55], 0, v[156:157]
	global_load_dwordx4 v[22:25], v[22:23], off nt
	s_cmpk_gt_u32 s24, 0x7d
	global_load_dwordx4 v[30:33], v[30:31], off nt
	s_waitcnt vmcnt(16)
	v_lshlrev_b32_e32 v228, 16, v240
	global_load_dwordx4 v[34:37], v[34:35], off nt
	v_and_b32_e32 v229, 0xffff0000, v240
	global_load_dwordx4 v[38:41], v[38:39], off nt
	v_lshlrev_b32_e32 v192, 16, v249
	global_load_dwordx4 v[42:45], v[42:43], off nt
	v_and_b32_e32 v193, 0xffff0000, v249
	global_load_dwordx4 v[46:49], v[46:47], off nt
	v_lshlrev_b32_e32 v202, 16, v248
	global_load_dwordx4 v[50:53], v[50:51], off nt
	v_and_b32_e32 v203, 0xffff0000, v248
	global_load_dwordx4 v[54:57], v[54:55], off nt
	s_waitcnt vmcnt(22)
	ds_write2_b64 v159, v[58:59], v[60:61] offset1:1
	ds_write2_b64 v160, v[62:63], v[64:65] offset1:1
	ds_write2_b64 v162, v[66:67], v[68:69] offset1:1
	ds_write2_b64 v163, v[70:71], v[72:73] offset1:1
	ds_write2_b64 v165, v[74:75], v[76:77] offset1:1
	ds_write2_b64 v166, v[78:79], v[80:81] offset1:1
	ds_write2_b64 v168, v[82:83], v[84:85] offset1:1
	ds_write2_b64 v169, v[86:87], v[88:89] offset1:1
	ds_write2_b64 v171, v[90:91], v[92:93] offset1:1
	ds_write2_b64 v173, v[94:95], v[96:97] offset1:1
	ds_write2_b64 v175, v[98:99], v[100:101] offset1:1
	ds_write2_b64 v177, v[102:103], v[104:105] offset1:1
	ds_write2_b64 v178, v[106:107], v[108:109] offset1:1
	ds_write2_b64 v179, v[110:111], v[112:113] offset1:1
	s_waitcnt lgkmcnt(0)
	s_barrier
; #define LAS __attribute__((address_space(3)))
; DI float lo_bf(unsigned u) { return __uint_as_float(u << 16); }
; DI float hi_bf(unsigned u) { return __uint_as_float(u & 0xffff0000u); }
; DI void scan_helper_step(const ScanH& k, int n, u32x4 (&stL)[14], const u32x4 (&stS)[14]) {
;     ...
;     const LAS unsigned char* ob = lds + SC_O + bf * SC_OSZ + k.pt * 272 + k.pseg * 64;
;     const LAS float* gmL = (const LAS float*)(lds + SC_O + 2 * SC_OSZ + 512) + 32 * k.pseg;
;     u32x4 ov4[4];
; #pragma unroll
;     for (int i = 0; i < 4; ++i) ov4[i] = *(const LAS u32x4*)(ob + 16 * i);
;     float ss = 0.f;
; #pragma unroll
;     for (int i = 0; i < 4; ++i)
; #pragma unroll
;         for (int j = 0; j < 4; ++j) { const float a = lo_bf(ov4[i][j]), b2 = hi_bf(ov4[i][j]); ss += a * a + b2 * b2; }
;     ss += __shfl_xor(ss, 1); ss += __shfl_xor(ss, 2);
;     const float rs = __builtin_amdgcn_rsqf(ss * (1.f / 128.f) + RMS_EPS);
	ds_read_b128 v[58:61], v185
	ds_read_b128 v[62:65], v185 offset:16
	ds_read_b128 v[66:69], v185 offset:32
	ds_read_b128 v[70:73], v185 offset:48
	v_lshlrev_b32_e32 v112, 16, v250
	s_waitcnt lgkmcnt(3)
	v_lshlrev_b32_e32 v198, 16, v58
	v_and_b32_e32 v199, 0xffff0000, v58
	s_waitcnt lgkmcnt(1)
	v_and_b32_e32 v87, 0xffff0000, v69
	v_and_b32_e32 v86, 0xffff0000, v68
	v_lshlrev_b32_e32 v85, 16, v69
	v_lshlrev_b32_e32 v84, 16, v68
	v_pk_mul_f32 v[68:69], v[86:87], v[86:87]
	s_waitcnt lgkmcnt(0)
	v_and_b32_e32 v93, 0xffff0000, v71
	v_and_b32_e32 v92, 0xffff0000, v70
	v_pk_fma_f32 v[88:89], v[84:85], v[84:85], v[68:69]
	v_lshlrev_b32_e32 v91, 16, v71
	v_lshlrev_b32_e32 v90, 16, v70
	v_pk_mul_f32 v[68:69], v[92:93], v[92:93]
	v_and_b32_e32 v99, 0xffff0000, v73
	v_and_b32_e32 v98, 0xffff0000, v72
	v_pk_fma_f32 v[94:95], v[90:91], v[90:91], v[68:69]
	v_lshlrev_b32_e32 v97, 16, v73
	v_lshlrev_b32_e32 v96, 16, v72
	v_pk_mul_f32 v[68:69], v[98:99], v[98:99]
	v_lshlrev_b32_e32 v108, 16, v60
	v_pk_fma_f32 v[100:101], v[96:97], v[96:97], v[68:69]
	v_lshlrev_b64 v[68:69], 11, v[188:189]
	v_lshlrev_b32_e32 v188, 16, v59
	v_and_b32_e32 v189, 0xffff0000, v59
	v_and_b32_e32 v109, 0xffff0000, v60
	v_pk_mul_f32 v[190:191], v[188:189], v[188:189]
	v_pk_mul_f32 v[200:201], v[198:199], v[198:199]
	v_lshlrev_b32_e32 v104, 16, v61
	v_and_b32_e32 v105, 0xffff0000, v61
	v_pk_mul_f32 v[110:111], v[108:109], v[108:109]
	v_add_f32_e32 v240, v190, v191
	v_add_f32_e32 v151, v200, v201
	v_pk_mul_f32 v[106:107], v[104:105], v[104:105]
	v_lshlrev_b32_e32 v218, 16, v62
	v_and_b32_e32 v219, 0xffff0000, v62
	v_add_f32_e32 v240, v151, v240
	v_add_f32_e32 v110, v110, v111
	v_lshlrev_b32_e32 v212, 16, v63
	v_and_b32_e32 v213, 0xffff0000, v63
	v_pk_mul_f32 v[62:63], v[218:219], v[218:219]
	v_add_f32_e32 v110, v110, v240
	v_add_f32_e32 v106, v106, v107
	v_lshlrev_b32_e32 v208, 16, v64
	v_and_b32_e32 v209, 0xffff0000, v64
	v_pk_mul_f32 v[214:215], v[212:213], v[212:213]
	v_add_f32_e32 v106, v106, v110
	v_add_f32_e32 v62, v62, v63
	v_and_b32_e32 v113, 0xffff0000, v250
	v_lshlrev_b32_e32 v248, 16, v251
	v_and_b32_e32 v249, 0xffff0000, v251
	v_lshlrev_b32_e32 v250, 16, v65
	v_and_b32_e32 v251, 0xffff0000, v65
	v_pk_mul_f32 v[64:65], v[208:209], v[208:209]
	v_add_f32_e32 v62, v62, v106
	v_add_f32_e32 v63, v214, v215
	v_pk_mul_f32 v[204:205], v[250:251], v[250:251]
	v_lshlrev_b32_e32 v224, 16, v66
	v_and_b32_e32 v225, 0xffff0000, v66
	v_add_f32_e32 v62, v63, v62
	v_add_f32_e32 v63, v64, v65
	v_lshlrev_b32_e32 v210, 16, v246
	v_and_b32_e32 v211, 0xffff0000, v246
	v_lshlrev_b32_e32 v216, 16, v245
	v_and_b32_e32 v217, 0xffff0000, v245
	v_lshlrev_b32_e32 v220, 16, v244
	v_and_b32_e32 v221, 0xffff0000, v244
	v_lshlrev_b32_e32 v244, 16, v247
	v_and_b32_e32 v245, 0xffff0000, v247
	v_lshlrev_b32_e32 v246, 16, v67
	v_and_b32_e32 v247, 0xffff0000, v67
	v_pk_mul_f32 v[66:67], v[224:225], v[224:225]
	v_add_f32_e32 v62, v63, v62
	v_add_f32_e32 v63, v204, v205
	v_pk_mul_f32 v[222:223], v[246:247], v[246:247]
	v_add_f32_e32 v62, v63, v62
	v_add_f32_e32 v63, v66, v67
	v_add_f32_e32 v62, v63, v62
	v_add_f32_e32 v63, v222, v223
	v_add_f32_e32 v62, v63, v62
	v_add_f32_e32 v62, v88, v62
	v_add_f32_e32 v62, v89, v62
	v_add_f32_e32 v62, v94, v62
	v_add_f32_e32 v62, v95, v62
	v_add_f32_e32 v62, v100, v62
	v_add_f32_e32 v62, v101, v62
	s_nop 1
	v_mov_b32_dpp v63, v62 quad_perm:[1,0,3,2] row_mask:0xf bank_mask:0xf
	v_lshl_add_u64 v[102:103], v[154:155], 0, v[68:69]
	ds_read_b128 v[68:71], v184
	ds_read_b128 v[72:75], v184 offset:16
	ds_read_b128 v[76:79], v184 offset:32
	ds_read_b128 v[80:83], v184 offset:48
	ds_read_b128 v[58:61], v184 offset:64
	ds_read_b128 v[130:133], v184 offset:80
	ds_read_b128 v[194:197], v184 offset:96
	ds_read_b128 v[232:235], v184 offset:112
	s_waitcnt lgkmcnt(5)
	v_add_f32_e32 v62, v62, v63
	s_nop 1
	v_mov_b32_dpp v63, v62 quad_perm:[2,3,0,1] row_mask:0xf bank_mask:0xf
	s_waitcnt lgkmcnt(0)
; DI unsigned pk2(float lo, float hi) { f32x2 v = {lo, hi}; bf16x2_t b = __builtin_convertvector(v, bf16x2_t); return __builtin_bit_cast(unsigned, b); }
; DI float lo_bf(unsigned u) { return __uint_as_float(u << 16); }
; DI float hi_bf(unsigned u) { return __uint_as_float(u & 0xffff0000u); }
; DI void scan_helper_step(const ScanH& k, int n, u32x4 (&stL)[14], const u32x4 (&stS)[14]) {
;     ...
;     const float rs = __builtin_amdgcn_rsqf(ss * (1.f / 128.f) + RMS_EPS);
;     bf16_t* mp = k.MIX + (size_t)(tokb + k.pt) * DM + k.h * 128 + 32 * k.pseg;
; #pragma unroll
;     for (int i = 0; i < 4; ++i) { u32x4 res;
; #pragma unroll
;         for (int j = 0; j < 4; ++j) { const int e = 8 * i + 2 * j;
;             const float a0 = lo_bf(ov4[i][j]) * rs * gmL[e] * lo_bf(zz[i][j]), a1 = hi_bf(ov4[i][j]) * rs * gmL[e + 1] * hi_bf(zz[i][j]); res[j] = pk2(a0, a1); }
;         *(u32x4*)(mp + 8 * i) = res; }
; DI void scan_item(LAS unsigned char* lds, const Ctx& c, int l, int bh) {
;     ...
;         for (int n = 0; n < 128; n += 2) {
;             scan_helper_step(k, n, stA, stB);
;             scan_helper_step(k, n + 1, stB, stA);
;         }
	v_add_f32_e32 v62, v62, v63
	v_fmamk_f32 v62, v62, 0x3c000000, v231
	v_rsq_f32_e32 v66, v62
	s_nop 0
	v_pk_mul_f32 v[62:63], v[66:67], v[198:199] op_sel_hi:[0,1]
	v_pk_mul_f32 v[64:65], v[66:67], v[188:189] op_sel_hi:[0,1]
	v_pk_mul_f32 v[62:63], v[68:69], v[62:63]
	v_pk_mul_f32 v[64:65], v[70:71], v[64:65]
	v_pk_mul_f32 v[62:63], v[62:63], v[202:203]
	v_pk_mul_f32 v[64:65], v[64:65], v[192:193]
	v_cvt_pk_bf16_f32 v62, v62, v63
	v_cvt_pk_bf16_f32 v63, v64, v65
	v_pk_mul_f32 v[64:65], v[66:67], v[108:109] op_sel_hi:[0,1]
	v_pk_mul_f32 v[68:69], v[66:67], v[104:105] op_sel_hi:[0,1]
	v_pk_mul_f32 v[64:65], v[72:73], v[64:65]
	v_pk_mul_f32 v[68:69], v[74:75], v[68:69]
	v_pk_mul_f32 v[64:65], v[64:65], v[112:113]
	v_pk_mul_f32 v[68:69], v[68:69], v[248:249]
	v_cvt_pk_bf16_f32 v64, v64, v65
	v_cvt_pk_bf16_f32 v65, v68, v69
	global_store_dwordx4 v[102:103], v[62:65], off
	v_pk_mul_f32 v[68:69], v[66:67], v[250:251] op_sel_hi:[0,1]
	v_pk_mul_f32 v[68:69], v[82:83], v[68:69]
	v_pk_mul_f32 v[62:63], v[66:67], v[218:219] op_sel_hi:[0,1]
	v_pk_mul_f32 v[64:65], v[66:67], v[212:213] op_sel_hi:[0,1]
	v_pk_mul_f32 v[62:63], v[76:77], v[62:63]
	v_pk_mul_f32 v[64:65], v[78:79], v[64:65]
	v_pk_mul_f32 v[62:63], v[62:63], v[220:221]
	v_pk_mul_f32 v[64:65], v[64:65], v[216:217]
	v_cvt_pk_bf16_f32 v62, v62, v63
	v_cvt_pk_bf16_f32 v63, v64, v65
	v_pk_mul_f32 v[64:65], v[66:67], v[208:209] op_sel_hi:[0,1]
	v_pk_mul_f32 v[64:65], v[80:81], v[64:65]
	v_pk_mul_f32 v[68:69], v[68:69], v[244:245]
	v_pk_mul_f32 v[64:65], v[64:65], v[210:211]
	s_nop 0
	v_cvt_pk_bf16_f32 v64, v64, v65
	v_cvt_pk_bf16_f32 v65, v68, v69
	global_store_dwordx4 v[102:103], v[62:65], off offset:16
	s_nop 1
	v_pk_mul_f32 v[62:63], v[66:67], v[224:225] op_sel_hi:[0,1]
	v_pk_mul_f32 v[58:59], v[58:59], v[62:63]
	v_pk_mul_f32 v[62:63], v[66:67], v[246:247] op_sel_hi:[0,1]
	v_pk_mul_f32 v[60:61], v[62:63], v[60:61]
	v_lshlrev_b32_e32 v62, 16, v241
	v_and_b32_e32 v63, 0xffff0000, v241
	v_pk_mul_f32 v[58:59], v[58:59], v[228:229]
	v_pk_mul_f32 v[60:61], v[60:61], v[62:63]
	v_cvt_pk_bf16_f32 v58, v58, v59
	v_cvt_pk_bf16_f32 v59, v60, v61
	v_mov_b32_e32 v60, v84
	v_mov_b32_e32 v61, v86
	v_pk_mul_f32 v[64:65], v[66:67], v[60:61] op_sel_hi:[0,1]
	v_mov_b32_e32 v86, v85
	s_waitcnt lgkmcnt(0)
	v_pk_mul_f32 v[60:61], v[64:65], v[130:131]
	v_lshlrev_b32_e32 v64, 16, v242
	v_and_b32_e32 v65, 0xffff0000, v242
	v_pk_mul_f32 v[60:61], v[60:61], v[64:65]
	v_pk_mul_f32 v[64:65], v[66:67], v[86:87] op_sel_hi:[0,1]
	v_pk_mul_f32 v[62:63], v[64:65], v[132:133]
	v_lshlrev_b32_e32 v64, 16, v243
	v_and_b32_e32 v65, 0xffff0000, v243
	v_pk_mul_f32 v[62:63], v[62:63], v[64:65]
	v_cvt_pk_bf16_f32 v60, v60, v61
	v_cvt_pk_bf16_f32 v61, v62, v63
	global_store_dwordx4 v[102:103], v[58:61], off offset:32
	s_nop 1
	v_mov_b32_e32 v58, v90
	v_mov_b32_e32 v59, v92
	v_pk_mul_f32 v[62:63], v[66:67], v[58:59] op_sel_hi:[0,1]
	v_mov_b32_e32 v92, v91
	s_waitcnt lgkmcnt(0)
	v_pk_mul_f32 v[58:59], v[62:63], v[194:195]
	v_lshlrev_b32_e32 v62, 16, v236
	v_and_b32_e32 v63, 0xffff0000, v236
	v_pk_mul_f32 v[58:59], v[58:59], v[62:63]
	v_pk_mul_f32 v[62:63], v[66:67], v[92:93] op_sel_hi:[0,1]
	v_pk_mul_f32 v[60:61], v[62:63], v[196:197]
	v_lshlrev_b32_e32 v62, 16, v237
	v_and_b32_e32 v63, 0xffff0000, v237
	v_pk_mul_f32 v[60:61], v[60:61], v[62:63]
	v_cvt_pk_bf16_f32 v58, v58, v59
	v_cvt_pk_bf16_f32 v59, v60, v61
	v_mov_b32_e32 v60, v96
	v_mov_b32_e32 v61, v98
	v_pk_mul_f32 v[64:65], v[66:67], v[60:61] op_sel_hi:[0,1]
	v_mov_b32_e32 v98, v97
	s_waitcnt lgkmcnt(0)
	v_pk_mul_f32 v[60:61], v[64:65], v[232:233]
	v_lshlrev_b32_e32 v64, 16, v238
	v_and_b32_e32 v65, 0xffff0000, v238
	v_pk_mul_f32 v[60:61], v[60:61], v[64:65]
	v_pk_mul_f32 v[64:65], v[66:67], v[98:99] op_sel_hi:[0,1]
	v_pk_mul_f32 v[62:63], v[64:65], v[234:235]
	v_lshlrev_b32_e32 v64, 16, v239
	v_and_b32_e32 v65, 0xffff0000, v239
	v_pk_mul_f32 v[62:63], v[62:63], v[64:65]
	v_cvt_pk_bf16_f32 v60, v60, v61
	v_cvt_pk_bf16_f32 v61, v62, v63
	global_store_dwordx4 v[102:103], v[58:61], off offset:48
	s_cbranch_scc0 .LBB0_198
	s_waitcnt vmcnt(0)
	s_setprio 0
	v_mov_b32_e32 v130, v1
	v_mov_b32_e32 v131, v1
	v_mov_b32_e32 v132, v1
	v_mov_b32_e32 v133, v1
	v_mov_b64_e32 v[194:195], 0x200
	v_mov_b64_e32 v[196:197], 0x1ff
	v_mov_b64_e32 v[232:233], 0x17f
	v_mov_b32_e32 v234, 0xc00
	v_mov_b32_e32 v235, 1
	v_mov_b64_e32 v[250:251], 0xaff
